# layer 1 w_in GEMM: tiles enumerated without the 48 skipped context-row tiles, the last 48 real tiles split 3-way along K (12/10/10 k-tiles on 144 workgroups) instead of 2-way over a round that still c
# baseline (speedup 1.0000x reference)
.LBB0_451:
	v_readlane_b32 s8, v254, 60
	v_readlane_b32 s9, v254, 61
	s_mov_b64 s[0:1], s[88:89]
	s_and_b64 vcc, exec, s[8:9]
	s_cbranch_vccnz .LBB0_640
	s_load_dwordx2 s[34:35], s[0:1], 0xd0
	s_load_dwordx2 s[36:37], s[0:1], 0x100
	s_load_dwordx8 s[20:27], s[0:1], 0x110
	s_load_dwordx2 s[38:39], s[0:1], 0x148
	v_readlane_b32 s54, v254, 0
	v_readlane_b32 s98, v254, 1
	s_movk_i32 s99, 0x660
	s_cmpk_eq_u32 s98, 0x100
	s_cbranch_scc0 .Lgi_sk_bnd
	s_movk_i32 s99, 0x6c0
	v_readlane_b32 s98, v255, 0
	s_cmp_eq_u32 s98, 1
	s_cselect_b32 s99, 0x690, s99
.Lgi_sk_bnd:
	s_branch .LBB0_455
.LBB0_453:
	s_or_b64 exec, exec, s[10:11]

.LBB0_455:
	s_mov_b32 s57, s54
	s_mov_b32 s55, 0
	s_mov_b32 s84, 0
	s_mov_b32 s85, 28
	s_cmpk_lt_i32 s99, 0x690
	s_cbranch_scc1 .Lgi_sk_dec
	v_readlane_b32 s0, v255, 0
	s_cmp_eq_u32 s0, 0
	s_cbranch_scc0 .Lgi_sk_l1
	s_cmpk_lt_i32 s54, 0x600
	s_cbranch_scc1 .Lgi_sk_dec
	s_mov_b32 s85, 14
	s_mov_b32 s55, 1
	s_sub_u32 s48, s54, 0x600
	s_cmpk_lt_i32 s54, 0x660
	s_cbranch_scc1 .Lgi_sk_dec
	s_mov_b32 s55, 2
	s_mov_b32 s85, 10
	s_movk_i32 s84, 0x900
	s_sub_u32 s57, s54, 96
	s_sub_u32 s48, s57, 0x600
	s_branch .Lgi_sk_dec
.Lgi_sk_l1:
	s_cmpk_lt_i32 s54, 0x600
	s_cbranch_scc1 .Lgi_sk_rm
	s_sub_u32 s48, s54, 0x600
	s_mov_b32 s55, 1
	s_mov_b32 s85, 8
	s_cmpk_lt_u32 s48, 48
	s_cbranch_scc1 .Lgi_sk_t
	s_sub_u32 s48, s48, 48
	s_mov_b32 s55, 2
	s_mov_b32 s85, 6
	s_movk_i32 s84, 0x600
	s_cmpk_lt_u32 s48, 48
	s_cbranch_scc1 .Lgi_sk_t
	s_sub_u32 s48, s48, 48
	s_movk_i32 s84, 0xb00
.Lgi_sk_t:
	s_add_u32 s57, s48, 0x600
.Lgi_sk_rm:
	s_mul_i32 s0, s57, 0x5051
	s_lshr_b32 s0, s0, 22
	s_mul_i32 s1, s0, 204
	s_sub_u32 s1, s57, s1
	s_lshl_b32 s1, s1, 3
	s_add_u32 s57, s1, s0

.LBB0_462:
	s_or_b64 exec, exec, s[0:1]
	s_cmp_eq_u32 s55, 0
	s_cbranch_scc1 .Lgi_sk_epi
	v_readlane_b32 s57, v255, 0
	s_lshl_b32 s32, s48, 18
	s_cmp_eq_u32 s57, 0
	s_cbranch_scc1 .Lgi_sk_l0
	s_lshl_b32 s32, s48, 19
	s_cmpk_eq_u32 s84, 0xb00
	s_cselect_b32 s98, 0x40000, 0
	s_add_u32 s32, s32, s98
.Lgi_sk_l0:
	s_load_dwordx2 s[94:95], s[88:89], 0x168
	s_load_dwordx2 s[84:85], s[88:89], 0x170
	v_lshrrev_b32_e32 v170, 6, v167
	v_and_b32_e32 v171, 63, v167
	v_lshlrev_b32_e32 v170, 15, v170
	v_lshl_add_u32 v170, v171, 4, v170
	s_lshl_b32 s57, s48, 2
	v_mov_b32_e32 v171, s57
	v_readfirstlane_b32 s98, v167
	s_waitcnt lgkmcnt(0)
	s_add_u32 s94, s94, s32
	s_addc_u32 s95, s95, 0
	s_cmp_eq_u32 s55, 2
	s_cbranch_scc0 .Lgi_sk_fin
	s_nop 7
	s_nop 7
	global_store_dwordx4 v170, v[0:3], s[94:95] sc0 sc1
	global_store_dwordx4 v170, v[4:7], s[94:95] offset:1024 sc0 sc1
	global_store_dwordx4 v170, v[8:11], s[94:95] offset:2048 sc0 sc1
	global_store_dwordx4 v170, v[12:15], s[94:95] offset:3072 sc0 sc1
	v_add_u32_e32 v170, 0x1000, v170
	global_store_dwordx4 v170, v[16:19], s[94:95] sc0 sc1
	global_store_dwordx4 v170, v[20:23], s[94:95] offset:1024 sc0 sc1
	global_store_dwordx4 v170, v[24:27], s[94:95] offset:2048 sc0 sc1
	global_store_dwordx4 v170, v[28:31], s[94:95] offset:3072 sc0 sc1
	v_add_u32_e32 v170, 0x1000, v170
	global_store_dwordx4 v170, v[32:35], s[94:95] sc0 sc1
	global_store_dwordx4 v170, v[36:39], s[94:95] offset:1024 sc0 sc1
	global_store_dwordx4 v170, v[40:43], s[94:95] offset:2048 sc0 sc1
	global_store_dwordx4 v170, v[44:47], s[94:95] offset:3072 sc0 sc1
	v_add_u32_e32 v170, 0x1000, v170
	global_store_dwordx4 v170, v[48:51], s[94:95] sc0 sc1
	global_store_dwordx4 v170, v[52:55], s[94:95] offset:1024 sc0 sc1
	global_store_dwordx4 v170, v[56:59], s[94:95] offset:2048 sc0 sc1
	global_store_dwordx4 v170, v[60:63], s[94:95] offset:3072 sc0 sc1
	v_add_u32_e32 v170, 0x1000, v170
	global_store_dwordx4 v170, v[64:67], s[94:95] sc0 sc1
	global_store_dwordx4 v170, v[68:71], s[94:95] offset:1024 sc0 sc1
	global_store_dwordx4 v170, v[72:75], s[94:95] offset:2048 sc0 sc1
	global_store_dwordx4 v170, v[76:79], s[94:95] offset:3072 sc0 sc1
	v_add_u32_e32 v170, 0x1000, v170
	global_store_dwordx4 v170, v[80:83], s[94:95] sc0 sc1
	global_store_dwordx4 v170, v[84:87], s[94:95] offset:1024 sc0 sc1
	global_store_dwordx4 v170, v[88:91], s[94:95] offset:2048 sc0 sc1
	global_store_dwordx4 v170, v[92:95], s[94:95] offset:3072 sc0 sc1
	v_add_u32_e32 v170, 0x1000, v170
	global_store_dwordx4 v170, v[96:99], s[94:95] sc0 sc1
	global_store_dwordx4 v170, v[100:103], s[94:95] offset:1024 sc0 sc1
	global_store_dwordx4 v170, v[104:107], s[94:95] offset:2048 sc0 sc1
	global_store_dwordx4 v170, v[108:111], s[94:95] offset:3072 sc0 sc1
	v_add_u32_e32 v170, 0x1000, v170
	global_store_dwordx4 v170, v[112:115], s[94:95] sc0 sc1
	global_store_dwordx4 v170, v[116:119], s[94:95] offset:1024 sc0 sc1
	global_store_dwordx4 v170, v[120:123], s[94:95] offset:2048 sc0 sc1
	global_store_dwordx4 v170, v[124:127], s[94:95] offset:3072 sc0 sc1
	v_add_u32_e32 v170, 0x1000, v170
	s_waitcnt vmcnt(0)
	s_barrier
	s_cmp_lt_u32 s98, 64
	s_cbranch_scc0 .Lgi_sk_tile_end
	s_mov_b64 exec, 1
	v_mov_b32_e32 v172, 1
	global_atomic_add v171, v172, s[84:85]
	s_waitcnt vmcnt(0)
	s_mov_b64 exec, -1
	s_branch .Lgi_sk_tile_end
.Lgi_sk_fin:
	s_cmp_lt_u32 s98, 64
	s_cbranch_scc0 .Lgi_sk_wd
	v_readlane_b32 s57, v255, 0
	s_lshl_b32 s57, s57, 1
	s_add_u32 s57, s57, 1
	s_mov_b32 s32, 0

.Lgi_sk_wd:
	s_barrier
	v_readlane_b32 s57, v255, 0
	s_add_u32 s57, s57, 1
.Lgi_sk_addloop:
	global_load_dwordx4 v[194:197], v170, s[94:95] sc0 sc1
	global_load_dwordx4 v[198:201], v170, s[94:95] offset:1024 sc0 sc1
	global_load_dwordx4 v[202:205], v170, s[94:95] offset:2048 sc0 sc1
	global_load_dwordx4 v[206:209], v170, s[94:95] offset:3072 sc0 sc1
	v_add_u32_e32 v170, 0x1000, v170
	global_load_dwordx4 v[210:213], v170, s[94:95] sc0 sc1
	global_load_dwordx4 v[214:217], v170, s[94:95] offset:1024 sc0 sc1
	global_load_dwordx4 v[218:221], v170, s[94:95] offset:2048 sc0 sc1
	global_load_dwordx4 v[222:225], v170, s[94:95] offset:3072 sc0 sc1
	v_add_u32_e32 v170, 0x1000, v170
	global_load_dwordx4 v[226:229], v170, s[94:95] sc0 sc1
	global_load_dwordx4 v[230:233], v170, s[94:95] offset:1024 sc0 sc1
	global_load_dwordx4 v[234:237], v170, s[94:95] offset:2048 sc0 sc1
	global_load_dwordx4 v[238:241], v170, s[94:95] offset:3072 sc0 sc1
	v_add_u32_e32 v170, 0x1000, v170
	global_load_dwordx4 v[242:245], v170, s[94:95] sc0 sc1
	global_load_dwordx4 v[246:249], v170, s[94:95] offset:1024 sc0 sc1
	global_load_dwordx4 v[250:253], v170, s[94:95] offset:2048 sc0 sc1
	s_waitcnt vmcnt(7)
	v_pk_add_f32 v[0:1], v[0:1], v[194:195]
	v_pk_add_f32 v[2:3], v[2:3], v[196:197]
	v_pk_add_f32 v[4:5], v[4:5], v[198:199]
	v_pk_add_f32 v[6:7], v[6:7], v[200:201]
	v_pk_add_f32 v[8:9], v[8:9], v[202:203]
	v_pk_add_f32 v[10:11], v[10:11], v[204:205]
	v_pk_add_f32 v[12:13], v[12:13], v[206:207]
	v_pk_add_f32 v[14:15], v[14:15], v[208:209]
	v_pk_add_f32 v[16:17], v[16:17], v[210:211]
	v_pk_add_f32 v[18:19], v[18:19], v[212:213]
	v_pk_add_f32 v[20:21], v[20:21], v[214:215]
	v_pk_add_f32 v[22:23], v[22:23], v[216:217]
	v_pk_add_f32 v[24:25], v[24:25], v[218:219]
	v_pk_add_f32 v[26:27], v[26:27], v[220:221]
	v_pk_add_f32 v[28:29], v[28:29], v[222:223]
	v_pk_add_f32 v[30:31], v[30:31], v[224:225]
	global_load_dwordx4 v[194:197], v170, s[94:95] offset:3072 sc0 sc1
	v_add_u32_e32 v170, 0x1000, v170
	global_load_dwordx4 v[198:201], v170, s[94:95] sc0 sc1
	global_load_dwordx4 v[202:205], v170, s[94:95] offset:1024 sc0 sc1
	global_load_dwordx4 v[206:209], v170, s[94:95] offset:2048 sc0 sc1
	global_load_dwordx4 v[210:213], v170, s[94:95] offset:3072 sc0 sc1
	v_add_u32_e32 v170, 0x1000, v170
	global_load_dwordx4 v[214:217], v170, s[94:95] sc0 sc1
	global_load_dwordx4 v[218:221], v170, s[94:95] offset:1024 sc0 sc1
	global_load_dwordx4 v[222:225], v170, s[94:95] offset:2048 sc0 sc1
	s_waitcnt vmcnt(8)
	v_pk_add_f32 v[32:33], v[32:33], v[226:227]
	v_pk_add_f32 v[34:35], v[34:35], v[228:229]
	v_pk_add_f32 v[36:37], v[36:37], v[230:231]
	v_pk_add_f32 v[38:39], v[38:39], v[232:233]
	v_pk_add_f32 v[40:41], v[40:41], v[234:235]
	v_pk_add_f32 v[42:43], v[42:43], v[236:237]
	v_pk_add_f32 v[44:45], v[44:45], v[238:239]
	v_pk_add_f32 v[46:47], v[46:47], v[240:241]
	v_pk_add_f32 v[48:49], v[48:49], v[242:243]
	v_pk_add_f32 v[50:51], v[50:51], v[244:245]
	v_pk_add_f32 v[52:53], v[52:53], v[246:247]
	v_pk_add_f32 v[54:55], v[54:55], v[248:249]
	v_pk_add_f32 v[56:57], v[56:57], v[250:251]
	v_pk_add_f32 v[58:59], v[58:59], v[252:253]
	global_load_dwordx4 v[226:229], v170, s[94:95] offset:3072 sc0 sc1
	v_add_u32_e32 v170, 0x1000, v170
	global_load_dwordx4 v[230:233], v170, s[94:95] sc0 sc1
	global_load_dwordx4 v[234:237], v170, s[94:95] offset:1024 sc0 sc1
	global_load_dwordx4 v[238:241], v170, s[94:95] offset:2048 sc0 sc1
	global_load_dwordx4 v[242:245], v170, s[94:95] offset:3072 sc0 sc1
	v_add_u32_e32 v170, 0x1000, v170
	global_load_dwordx4 v[246:249], v170, s[94:95] sc0 sc1
	global_load_dwordx4 v[250:253], v170, s[94:95] offset:1024 sc0 sc1
	s_waitcnt vmcnt(7)
	v_pk_add_f32 v[60:61], v[60:61], v[194:195]
	v_pk_add_f32 v[62:63], v[62:63], v[196:197]
	v_pk_add_f32 v[64:65], v[64:65], v[198:199]
	v_pk_add_f32 v[66:67], v[66:67], v[200:201]
	v_pk_add_f32 v[68:69], v[68:69], v[202:203]
	v_pk_add_f32 v[70:71], v[70:71], v[204:205]
	v_pk_add_f32 v[72:73], v[72:73], v[206:207]
	v_pk_add_f32 v[74:75], v[74:75], v[208:209]
	v_pk_add_f32 v[76:77], v[76:77], v[210:211]
	v_pk_add_f32 v[78:79], v[78:79], v[212:213]
	v_pk_add_f32 v[80:81], v[80:81], v[214:215]
	v_pk_add_f32 v[82:83], v[82:83], v[216:217]
	v_pk_add_f32 v[84:85], v[84:85], v[218:219]
	v_pk_add_f32 v[86:87], v[86:87], v[220:221]
	v_pk_add_f32 v[88:89], v[88:89], v[222:223]
	v_pk_add_f32 v[90:91], v[90:91], v[224:225]
	global_load_dwordx4 v[194:197], v170, s[94:95] offset:2048 sc0 sc1
	global_load_dwordx4 v[198:201], v170, s[94:95] offset:3072 sc0 sc1
	v_add_u32_e32 v170, 0x1000, v170
	s_waitcnt vmcnt(2)
	v_pk_add_f32 v[92:93], v[92:93], v[226:227]
	v_pk_add_f32 v[94:95], v[94:95], v[228:229]
	v_pk_add_f32 v[96:97], v[96:97], v[230:231]
	v_pk_add_f32 v[98:99], v[98:99], v[232:233]
	v_pk_add_f32 v[100:101], v[100:101], v[234:235]
	v_pk_add_f32 v[102:103], v[102:103], v[236:237]
	v_pk_add_f32 v[104:105], v[104:105], v[238:239]
	v_pk_add_f32 v[106:107], v[106:107], v[240:241]
	v_pk_add_f32 v[108:109], v[108:109], v[242:243]
	v_pk_add_f32 v[110:111], v[110:111], v[244:245]
	v_pk_add_f32 v[112:113], v[112:113], v[246:247]
	v_pk_add_f32 v[114:115], v[114:115], v[248:249]
	v_pk_add_f32 v[116:117], v[116:117], v[250:251]
	v_pk_add_f32 v[118:119], v[118:119], v[252:253]
	s_waitcnt vmcnt(0)
	v_pk_add_f32 v[120:121], v[120:121], v[194:195]
	v_pk_add_f32 v[122:123], v[122:123], v[196:197]
	v_pk_add_f32 v[124:125], v[124:125], v[198:199]
	v_pk_add_f32 v[126:127], v[126:127], v[200:201]
	s_sub_u32 s57, s57, 1
	s_cmp_eq_u32 s57, 0
	s_cbranch_scc1 .Lgi_sk_epi
	s_add_u32 s94, s94, 0x40000
	s_addc_u32 s95, s95, 0
	v_add_u32_e32 v170, 0xffff8000, v170
	s_branch .Lgi_sk_addloop
